# P4 epilogue de-serialised + P1 unit order rebalanced (one gelu/V epilogue per workgroup)
# speedup vs baseline: 1.0043x; 1.0005x over previous
.LBB0_115:
	s_add_i32 s61, s57, 1
	s_cmp_lt_u32 s57, 2
	s_cselect_b64 s[68:69], -1, 0
	s_cmp_gt_u32 s57, 1
	s_cbranch_scc1 .LBB0_120
	s_and_b64 vcc, exec, s[52:53]
	s_cbranch_vccz .Lp1_order_lo
	s_cmp_eq_u32 s61, 2
	s_cselect_b32 s21, 0, -4
	s_cselect_b32 s63, 2, 1
	s_add_i32 s66, s55, s21
	s_branch .LBB0_120
.Lp1_order_lo:
	s_cmp_eq_u32 s57, 0
	s_cselect_b32 s21, 4, 0
	s_cselect_b32 s63, 3, 2
	s_or_b32 s66, s21, s55
